# rw_scan loop variant B: waves 0-3 hold 2 rows x 8 keys per thread, 8-lane reductions (fewer DPP ops per element)
# speedup vs baseline: 1.0421x; 1.0131x over previous
; #define RW_GLOAD(ck) do { const int row_ = seq_row(b, dir, (ck) * 64 + tok); gr = *(const u32x4*)(R + (size_t)row_ * D + ch0); gk = *(const u32x4*)(Kx + (size_t)row_ * D + ch0); gv = *(const u32x4*)(Vx + (size_t)row_ * D + ch0); \
;         gw = *(const u32x4*)(W + ((size_t)row_ * 2 + dir) * D + ch0); ga = *(const u32x4*)(AD + ((size_t)row_ * 2 + dir) * D + ch0); } while (0)
; __device__ __forceinline__ void phase_rw_scan(KP P, const Ctx& c) {
;     ...
;         const int b = chain >> 6, hd = (chain >> 1) & 31, dir = chain & 1;
;         bf16_t* Y = (bf16_t*)(P->ws + (dir ? L_Y1 : L_Y0));
;         const int ch0 = hd * 64 + cq * 8;
;         float kkw[8], kaw[8];
; #pragma unroll
;         for (int j = 0; j < 8; ++j) { kkw[j] = P->in[I_RWKK][ch0 + j]; kaw[j] = P->in[I_RWKA][ch0 + j]; }
;         float s[8] = {0.f, 0.f, 0.f, 0.f, 0.f, 0.f, 0.f, 0.f};
;         u32x4 gr, gk, gv, gw, ga;
;     ...
;         RW_GLOAD(0);
.LBB0_1753:
	s_or_b64 exec, exec, s[48:49]
	s_waitcnt vmcnt(7)
	v_ashrrev_i32_e32 v27, 31, v26
	v_lshlrev_b64 v[28:29], 12, v[26:27]
	s_waitcnt vmcnt(5)
	v_lshlrev_b64 v[34:35], 13, v[26:27]
	v_lshl_add_u64 v[20:21], s[40:41], 0, v[28:29]
	v_lshlrev_b32_e32 v118, 1, v18
	v_lshl_or_b32 v34, s5, 12, v34
	v_lshl_add_u64 v[18:19], v[20:21], 0, v[118:119]
	v_lshl_add_u64 v[20:21], s[42:43], 0, v[28:29]
	v_lshl_add_u64 v[28:29], s[50:51], 0, v[28:29]
	v_lshl_add_u64 v[26:27], s[56:57], 0, v[34:35]
	v_lshl_add_u64 v[34:35], s[58:59], 0, v[34:35]
	v_lshl_add_u64 v[22:23], v[20:21], 0, v[118:119]
	v_lshl_add_u64 v[28:29], v[28:29], 0, v[118:119]
	v_lshl_add_u64 v[30:31], v[26:27], 0, v[118:119]
	v_lshl_add_u64 v[34:35], v[34:35], 0, v[118:119]
	global_load_dwordx4 v[18:21], v[18:19], off
	s_nop 0
	global_load_dwordx4 v[22:25], v[22:23], off
	s_nop 0
	global_load_dwordx4 v[26:29], v[28:29], off
	s_nop 0
	global_load_dwordx4 v[30:33], v[30:31], off
	s_and_b64 s[8:9], s[46:47], exec
	global_load_dwordx4 v[34:37], v[34:35], off
	s_mov_b32 s8, 0x3cc00000
	s_cselect_b32 s9, s8, 0x45400000
	s_add_u32 s10, s38, s9
	s_waitcnt vmcnt(7)
	v_mov_b32_e32 v38, v6
	v_mov_b32_e32 v6, v8
	s_addc_u32 s11, s39, 0
	s_mov_b32 s8, 0
	s_lshl_b32 s5, s5, 11
	v_lshl_add_u64 v[122:123], s[40:41], 0, v[118:119]
	v_lshl_add_u64 v[124:125], s[42:43], 0, v[118:119]
	v_lshl_add_u64 v[126:127], s[50:51], 0, v[118:119]
	v_lshl_add_u64 v[128:129], s[56:57], 0, v[118:119]
	v_lshl_add_u64 v[130:131], s[58:59], 0, v[118:119]
	v_lshl_add_u64 v[132:133], s[10:11], 0, v[118:119]
	v_swap_b32 v8, v5
	v_mov_b32_e32 v6, v3
	v_mov_b32_e32 v3, v38
	v_mov_b32_e32 v118, 0
	v_mov_b32_e32 v161, 0
	v_mov_b32_e32 v162, 0
	v_mov_b32_e32 v163, 0
	v_mov_b32_e32 v164, 0
	v_mov_b32_e32 v165, 0
	v_mov_b32_e32 v166, 0
	v_mov_b32_e32 v167, 0
	v_mov_b32_e32 v170, 0
	v_mov_b32_e32 v171, 0
	v_mov_b32_e32 v172, 0
	v_mov_b32_e32 v173, 0
	v_mov_b32_e32 v174, 0
	v_mov_b32_e32 v175, 0
	v_mov_b32_e32 v176, 0
	v_mov_b32_e32 v177, 0
	v_mov_b32_e32 v178, 0
	v_mov_b32_e32 v179, 0
	v_mov_b32_e32 v180, 0
	v_mov_b32_e32 v181, 0
	v_mov_b32_e32 v182, 0
	v_mov_b32_e32 v183, 0
	v_mov_b32_e32 v184, 0
	v_mov_b32_e32 v185, 0
	s_branch .LBB0_1755

; __device__ __forceinline__ void phase_rw_scan(KP P, const Ctx& c) {
;     ...
;             RW_LLOAD(A, 0);
; #pragma unroll 1
;             for (int tk = 0; tk < 64; tk += 2) {
;                 RW_LLOAD(B, tk + 1);
;                 RW_STEP(A, tk);
;                 RW_LLOAD(A, (tk + 2) & 63);
;                 RW_STEP(B, tk + 1);
;             }
.LBB0_1759:
	v_readfirstlane_b32 s63, v0
	v_and_b32_e32 v240, 7, v0
	v_lshrrev_b32_e32 v242, 3, v0
	s_cmpk_ge_u32 s63, 0x100
	s_cbranch_scc1 .LBB0_1754
	v_cmp_eq_u32_e64 s[60:61], 0, v240
	v_lshlrev_b32_e32 v240, 5, v240
	v_lshlrev_b32_e32 v242, 3, v242
	v_add_u32_e32 v241, 0x10000, v240
	v_add_u32_e32 v242, 0x14000, v242
	v_mov_b32_e32 v243, 0x1c000
	s_mov_b32 s62, 0
	ds_read_b128 v[38:41], v240 offset:32768
	ds_read_b128 v[42:45], v240 offset:32784
	ds_read_b128 v[46:49], v240 offset:0
	ds_read_b128 v[50:53], v240 offset:16
	ds_read_b128 v[54:57], v240 offset:16384
	ds_read_b128 v[58:61], v240 offset:16400
	ds_read_b128 v[62:65], v241 offset:0
	ds_read_b128 v[66:69], v241 offset:16
	ds_read_b64 v[78:79], v242 offset:0
	ds_read_b128 v[70:73], v240 offset:49152
	ds_read_b128 v[74:77], v240 offset:49168
	ds_read_b64 v[80:81], v243 offset:0
	ds_read_b32 v245, v243
.Lrw_loop:
	s_waitcnt lgkmcnt(9)
	v_pk_mul_f32 v[230:231], v[170:171], v[38:39] op_sel_hi:[1,0]
	v_pk_mul_f32 v[232:233], v[170:171], v[46:47] op_sel_hi:[1,0]
	v_pk_fma_f32 v[230:231], v[172:173], v[38:39], v[230:231] op_sel:[0,1,0]
	v_pk_fma_f32 v[232:233], v[172:173], v[46:47], v[232:233] op_sel:[0,1,0]
	v_pk_fma_f32 v[230:231], v[174:175], v[40:41], v[230:231] op_sel_hi:[1,0,1]
	v_pk_fma_f32 v[232:233], v[174:175], v[48:49], v[232:233] op_sel_hi:[1,0,1]
	v_pk_fma_f32 v[230:231], v[176:177], v[40:41], v[230:231] op_sel:[0,1,0]
	v_pk_fma_f32 v[232:233], v[176:177], v[48:49], v[232:233] op_sel:[0,1,0]
	v_pk_fma_f32 v[230:231], v[178:179], v[42:43], v[230:231] op_sel_hi:[1,0,1]
	v_pk_fma_f32 v[232:233], v[178:179], v[50:51], v[232:233] op_sel_hi:[1,0,1]
	v_pk_fma_f32 v[230:231], v[180:181], v[42:43], v[230:231] op_sel:[0,1,0]
	v_pk_fma_f32 v[232:233], v[180:181], v[50:51], v[232:233] op_sel:[0,1,0]
	v_pk_fma_f32 v[230:231], v[182:183], v[44:45], v[230:231] op_sel_hi:[1,0,1]
	v_pk_fma_f32 v[232:233], v[182:183], v[52:53], v[232:233] op_sel_hi:[1,0,1]
	v_pk_fma_f32 v[230:231], v[184:185], v[44:45], v[230:231] op_sel:[0,1,0]
	v_pk_fma_f32 v[232:233], v[184:185], v[52:53], v[232:233] op_sel:[0,1,0]
	ds_read_b128 v[186:189], v240 offset:33024
	ds_read_b128 v[190:193], v240 offset:33040
	ds_read_b128 v[194:197], v240 offset:256
	ds_read_b128 v[198:201], v240 offset:272
	s_waitcnt lgkmcnt(8)
	v_pk_mul_f32 v[82:83], v[170:171], v[54:55] op_sel_hi:[1,0]
	v_pk_mul_f32 v[84:85], v[172:173], v[54:55] op_sel:[0,1]
	v_pk_mul_f32 v[86:87], v[174:175], v[56:57] op_sel_hi:[1,0]
	v_pk_mul_f32 v[88:89], v[176:177], v[56:57] op_sel:[0,1]
	v_add_f32_dpp v230, v230, v230 quad_perm:[1,0,3,2] row_mask:0xf bank_mask:0xf
	v_pk_mul_f32 v[90:91], v[178:179], v[58:59] op_sel_hi:[1,0]
	v_add_f32_dpp v231, v231, v231 quad_perm:[1,0,3,2] row_mask:0xf bank_mask:0xf
	v_pk_mul_f32 v[92:93], v[180:181], v[58:59] op_sel:[0,1]
	v_add_f32_dpp v232, v232, v232 quad_perm:[1,0,3,2] row_mask:0xf bank_mask:0xf
	v_pk_mul_f32 v[94:95], v[182:183], v[60:61] op_sel_hi:[1,0]
	v_add_f32_dpp v233, v233, v233 quad_perm:[1,0,3,2] row_mask:0xf bank_mask:0xf
	v_pk_mul_f32 v[96:97], v[184:185], v[60:61] op_sel:[0,1]
	v_add_f32_dpp v230, v230, v230 quad_perm:[2,3,0,1] row_mask:0xf bank_mask:0xf
	v_pk_fma_f32 v[82:83], v[78:79], v[62:63], v[82:83] op_sel_hi:[1,0,1]
	v_add_f32_dpp v231, v231, v231 quad_perm:[2,3,0,1] row_mask:0xf bank_mask:0xf
	v_pk_fma_f32 v[84:85], v[78:79], v[62:63], v[84:85] op_sel:[0,1,0]
	v_add_f32_dpp v232, v232, v232 quad_perm:[2,3,0,1] row_mask:0xf bank_mask:0xf
	v_pk_fma_f32 v[86:87], v[78:79], v[64:65], v[86:87] op_sel_hi:[1,0,1]
	v_add_f32_dpp v233, v233, v233 quad_perm:[2,3,0,1] row_mask:0xf bank_mask:0xf
	v_pk_fma_f32 v[88:89], v[78:79], v[64:65], v[88:89] op_sel:[0,1,0]
	v_add_f32_dpp v230, v230, v230 row_half_mirror row_mask:0xf bank_mask:0xf
	v_pk_fma_f32 v[90:91], v[78:79], v[66:67], v[90:91] op_sel_hi:[1,0,1]
	v_add_f32_dpp v231, v231, v231 row_half_mirror row_mask:0xf bank_mask:0xf
	v_pk_fma_f32 v[92:93], v[78:79], v[66:67], v[92:93] op_sel:[0,1,0]
	v_add_f32_dpp v232, v232, v232 row_half_mirror row_mask:0xf bank_mask:0xf
	v_pk_fma_f32 v[94:95], v[78:79], v[68:69], v[94:95] op_sel_hi:[1,0,1]
	v_add_f32_dpp v233, v233, v233 row_half_mirror row_mask:0xf bank_mask:0xf
	v_pk_fma_f32 v[96:97], v[78:79], v[68:69], v[96:97] op_sel:[0,1,0]
	ds_read_b128 v[202:205], v240 offset:16640
	ds_read_b128 v[206:209], v240 offset:16656
	ds_read_b128 v[210:213], v241 offset:256
	ds_read_b128 v[214:217], v241 offset:272
	ds_read_b64 v[226:227], v242 offset:256
	s_waitcnt lgkmcnt(10)
	v_pk_fma_f32 v[170:171], v[230:231], v[70:71], v[82:83] op_sel_hi:[1,0,1] neg_lo:[1,0,0] neg_hi:[1,0,0]
	v_pk_fma_f32 v[172:173], v[230:231], v[70:71], v[84:85] op_sel:[0,1,0] neg_lo:[1,0,0] neg_hi:[1,0,0]
	v_pk_fma_f32 v[174:175], v[230:231], v[72:73], v[86:87] op_sel_hi:[1,0,1] neg_lo:[1,0,0] neg_hi:[1,0,0]
	v_pk_fma_f32 v[176:177], v[230:231], v[72:73], v[88:89] op_sel:[0,1,0] neg_lo:[1,0,0] neg_hi:[1,0,0]
	v_pk_fma_f32 v[178:179], v[230:231], v[74:75], v[90:91] op_sel_hi:[1,0,1] neg_lo:[1,0,0] neg_hi:[1,0,0]
	v_pk_fma_f32 v[180:181], v[230:231], v[74:75], v[92:93] op_sel:[0,1,0] neg_lo:[1,0,0] neg_hi:[1,0,0]
	v_pk_fma_f32 v[182:183], v[230:231], v[76:77], v[94:95] op_sel_hi:[1,0,1] neg_lo:[1,0,0] neg_hi:[1,0,0]
	v_pk_fma_f32 v[184:185], v[230:231], v[76:77], v[96:97] op_sel:[0,1,0] neg_lo:[1,0,0] neg_hi:[1,0,0]
	v_pk_fma_f32 v[234:235], v[230:231], v[80:81], v[232:233] op_sel_hi:[1,0,1] neg_lo:[1,0,0] neg_hi:[1,0,0]
	v_pk_fma_f32 v[234:235], v[78:79], v[80:81], v[234:235] op_sel:[0,1,0]
	ds_read_b128 v[218:221], v240 offset:49408
	ds_read_b128 v[222:225], v240 offset:49424
	ds_read_b64 v[228:229], v243 offset:8
	s_mov_b64 exec, s[60:61]
	ds_write_b64 v242, v[234:235] offset:16384
	s_mov_b64 exec, -1
	s_waitcnt lgkmcnt(9)
; __device__ __forceinline__ void phase_rw_scan(KP P, const Ctx& c) {
;     ...
;             RW_LLOAD(A, 0);
; #pragma unroll 1
;             for (int tk = 0; tk < 64; tk += 2) {
;                 RW_LLOAD(B, tk + 1);
;                 RW_STEP(A, tk);
;                 RW_LLOAD(A, (tk + 2) & 63);
;                 RW_STEP(B, tk + 1);
;             }
	v_pk_mul_f32 v[230:231], v[170:171], v[186:187] op_sel_hi:[1,0]
	v_pk_mul_f32 v[232:233], v[170:171], v[194:195] op_sel_hi:[1,0]
	v_pk_fma_f32 v[230:231], v[172:173], v[186:187], v[230:231] op_sel:[0,1,0]
	v_pk_fma_f32 v[232:233], v[172:173], v[194:195], v[232:233] op_sel:[0,1,0]
	v_pk_fma_f32 v[230:231], v[174:175], v[188:189], v[230:231] op_sel_hi:[1,0,1]
	v_pk_fma_f32 v[232:233], v[174:175], v[196:197], v[232:233] op_sel_hi:[1,0,1]
	v_pk_fma_f32 v[230:231], v[176:177], v[188:189], v[230:231] op_sel:[0,1,0]
	v_pk_fma_f32 v[232:233], v[176:177], v[196:197], v[232:233] op_sel:[0,1,0]
	v_pk_fma_f32 v[230:231], v[178:179], v[190:191], v[230:231] op_sel_hi:[1,0,1]
	v_pk_fma_f32 v[232:233], v[178:179], v[198:199], v[232:233] op_sel_hi:[1,0,1]
	v_pk_fma_f32 v[230:231], v[180:181], v[190:191], v[230:231] op_sel:[0,1,0]
	v_pk_fma_f32 v[232:233], v[180:181], v[198:199], v[232:233] op_sel:[0,1,0]
	v_pk_fma_f32 v[230:231], v[182:183], v[192:193], v[230:231] op_sel_hi:[1,0,1]
	v_pk_fma_f32 v[232:233], v[182:183], v[200:201], v[232:233] op_sel_hi:[1,0,1]
	v_pk_fma_f32 v[230:231], v[184:185], v[192:193], v[230:231] op_sel:[0,1,0]
	v_pk_fma_f32 v[232:233], v[184:185], v[200:201], v[232:233] op_sel:[0,1,0]
	ds_read_b128 v[38:41], v240 offset:33280
	ds_read_b128 v[42:45], v240 offset:33296
	ds_read_b128 v[46:49], v240 offset:512
	ds_read_b128 v[50:53], v240 offset:528
	s_waitcnt lgkmcnt(8)
	v_pk_mul_f32 v[82:83], v[170:171], v[202:203] op_sel_hi:[1,0]
	v_pk_mul_f32 v[84:85], v[172:173], v[202:203] op_sel:[0,1]
	v_pk_mul_f32 v[86:87], v[174:175], v[204:205] op_sel_hi:[1,0]
	v_pk_mul_f32 v[88:89], v[176:177], v[204:205] op_sel:[0,1]
	v_add_f32_dpp v230, v230, v230 quad_perm:[1,0,3,2] row_mask:0xf bank_mask:0xf
	v_pk_mul_f32 v[90:91], v[178:179], v[206:207] op_sel_hi:[1,0]
	v_add_f32_dpp v231, v231, v231 quad_perm:[1,0,3,2] row_mask:0xf bank_mask:0xf
	v_pk_mul_f32 v[92:93], v[180:181], v[206:207] op_sel:[0,1]
	v_add_f32_dpp v232, v232, v232 quad_perm:[1,0,3,2] row_mask:0xf bank_mask:0xf
	v_pk_mul_f32 v[94:95], v[182:183], v[208:209] op_sel_hi:[1,0]
	v_add_f32_dpp v233, v233, v233 quad_perm:[1,0,3,2] row_mask:0xf bank_mask:0xf
	v_pk_mul_f32 v[96:97], v[184:185], v[208:209] op_sel:[0,1]
	v_add_f32_dpp v230, v230, v230 quad_perm:[2,3,0,1] row_mask:0xf bank_mask:0xf
	v_pk_fma_f32 v[82:83], v[226:227], v[210:211], v[82:83] op_sel_hi:[1,0,1]
	v_add_f32_dpp v231, v231, v231 quad_perm:[2,3,0,1] row_mask:0xf bank_mask:0xf
	v_pk_fma_f32 v[84:85], v[226:227], v[210:211], v[84:85] op_sel:[0,1,0]
	v_add_f32_dpp v232, v232, v232 quad_perm:[2,3,0,1] row_mask:0xf bank_mask:0xf
	v_pk_fma_f32 v[86:87], v[226:227], v[212:213], v[86:87] op_sel_hi:[1,0,1]
	v_add_f32_dpp v233, v233, v233 quad_perm:[2,3,0,1] row_mask:0xf bank_mask:0xf
	v_pk_fma_f32 v[88:89], v[226:227], v[212:213], v[88:89] op_sel:[0,1,0]
	v_add_f32_dpp v230, v230, v230 row_half_mirror row_mask:0xf bank_mask:0xf
	v_pk_fma_f32 v[90:91], v[226:227], v[214:215], v[90:91] op_sel_hi:[1,0,1]
	v_add_f32_dpp v231, v231, v231 row_half_mirror row_mask:0xf bank_mask:0xf
	v_pk_fma_f32 v[92:93], v[226:227], v[214:215], v[92:93] op_sel:[0,1,0]
	v_add_f32_dpp v232, v232, v232 row_half_mirror row_mask:0xf bank_mask:0xf
	v_pk_fma_f32 v[94:95], v[226:227], v[216:217], v[94:95] op_sel_hi:[1,0,1]
	v_add_f32_dpp v233, v233, v233 row_half_mirror row_mask:0xf bank_mask:0xf
	v_pk_fma_f32 v[96:97], v[226:227], v[216:217], v[96:97] op_sel:[0,1,0]
	ds_read_b128 v[54:57], v240 offset:16896
	ds_read_b128 v[58:61], v240 offset:16912
	ds_read_b128 v[62:65], v241 offset:512
	ds_read_b128 v[66:69], v241 offset:528
	ds_read_b64 v[78:79], v242 offset:512
	s_waitcnt lgkmcnt(10)
	v_pk_fma_f32 v[170:171], v[230:231], v[218:219], v[82:83] op_sel_hi:[1,0,1] neg_lo:[1,0,0] neg_hi:[1,0,0]
	v_pk_fma_f32 v[172:173], v[230:231], v[218:219], v[84:85] op_sel:[0,1,0] neg_lo:[1,0,0] neg_hi:[1,0,0]
	v_pk_fma_f32 v[174:175], v[230:231], v[220:221], v[86:87] op_sel_hi:[1,0,1] neg_lo:[1,0,0] neg_hi:[1,0,0]
	v_pk_fma_f32 v[176:177], v[230:231], v[220:221], v[88:89] op_sel:[0,1,0] neg_lo:[1,0,0] neg_hi:[1,0,0]
	v_pk_fma_f32 v[178:179], v[230:231], v[222:223], v[90:91] op_sel_hi:[1,0,1] neg_lo:[1,0,0] neg_hi:[1,0,0]
	v_pk_fma_f32 v[180:181], v[230:231], v[222:223], v[92:93] op_sel:[0,1,0] neg_lo:[1,0,0] neg_hi:[1,0,0]
	v_pk_fma_f32 v[182:183], v[230:231], v[224:225], v[94:95] op_sel_hi:[1,0,1] neg_lo:[1,0,0] neg_hi:[1,0,0]
	v_pk_fma_f32 v[184:185], v[230:231], v[224:225], v[96:97] op_sel:[0,1,0] neg_lo:[1,0,0] neg_hi:[1,0,0]
	v_pk_fma_f32 v[234:235], v[230:231], v[228:229], v[232:233] op_sel_hi:[1,0,1] neg_lo:[1,0,0] neg_hi:[1,0,0]
	v_pk_fma_f32 v[234:235], v[226:227], v[228:229], v[234:235] op_sel:[0,1,0]
	ds_read_b128 v[70:73], v240 offset:49664
	ds_read_b128 v[74:77], v240 offset:49680
	ds_read_b64 v[80:81], v243 offset:16
	s_mov_b64 exec, s[60:61]
	ds_write_b64 v242, v[234:235] offset:16640
	s_mov_b64 exec, -1
	s_waitcnt lgkmcnt(9)
	v_pk_mul_f32 v[230:231], v[170:171], v[38:39] op_sel_hi:[1,0]
	v_pk_mul_f32 v[232:233], v[170:171], v[46:47] op_sel_hi:[1,0]
	v_pk_fma_f32 v[230:231], v[172:173], v[38:39], v[230:231] op_sel:[0,1,0]
	v_pk_fma_f32 v[232:233], v[172:173], v[46:47], v[232:233] op_sel:[0,1,0]
	v_pk_fma_f32 v[230:231], v[174:175], v[40:41], v[230:231] op_sel_hi:[1,0,1]
	v_pk_fma_f32 v[232:233], v[174:175], v[48:49], v[232:233] op_sel_hi:[1,0,1]
	v_pk_fma_f32 v[230:231], v[176:177], v[40:41], v[230:231] op_sel:[0,1,0]
	v_pk_fma_f32 v[232:233], v[176:177], v[48:49], v[232:233] op_sel:[0,1,0]
	v_pk_fma_f32 v[230:231], v[178:179], v[42:43], v[230:231] op_sel_hi:[1,0,1]
	v_pk_fma_f32 v[232:233], v[178:179], v[50:51], v[232:233] op_sel_hi:[1,0,1]
	v_pk_fma_f32 v[230:231], v[180:181], v[42:43], v[230:231] op_sel:[0,1,0]
	v_pk_fma_f32 v[232:233], v[180:181], v[50:51], v[232:233] op_sel:[0,1,0]
	v_pk_fma_f32 v[230:231], v[182:183], v[44:45], v[230:231] op_sel_hi:[1,0,1]
	v_pk_fma_f32 v[232:233], v[182:183], v[52:53], v[232:233] op_sel_hi:[1,0,1]
	v_pk_fma_f32 v[230:231], v[184:185], v[44:45], v[230:231] op_sel:[0,1,0]
	v_pk_fma_f32 v[232:233], v[184:185], v[52:53], v[232:233] op_sel:[0,1,0]
	ds_read_b128 v[186:189], v240 offset:33536
	ds_read_b128 v[190:193], v240 offset:33552
	ds_read_b128 v[194:197], v240 offset:768
	ds_read_b128 v[198:201], v240 offset:784
	s_waitcnt lgkmcnt(8)
; __device__ __forceinline__ void phase_rw_scan(KP P, const Ctx& c) {
;     ...
;             RW_LLOAD(A, 0);
; #pragma unroll 1
;             for (int tk = 0; tk < 64; tk += 2) {
;                 RW_LLOAD(B, tk + 1);
;                 RW_STEP(A, tk);
;                 RW_LLOAD(A, (tk + 2) & 63);
;                 RW_STEP(B, tk + 1);
;             }
	v_pk_mul_f32 v[82:83], v[170:171], v[54:55] op_sel_hi:[1,0]
	v_pk_mul_f32 v[84:85], v[172:173], v[54:55] op_sel:[0,1]
	v_pk_mul_f32 v[86:87], v[174:175], v[56:57] op_sel_hi:[1,0]
	v_pk_mul_f32 v[88:89], v[176:177], v[56:57] op_sel:[0,1]
	v_add_f32_dpp v230, v230, v230 quad_perm:[1,0,3,2] row_mask:0xf bank_mask:0xf
	v_pk_mul_f32 v[90:91], v[178:179], v[58:59] op_sel_hi:[1,0]
	v_add_f32_dpp v231, v231, v231 quad_perm:[1,0,3,2] row_mask:0xf bank_mask:0xf
	v_pk_mul_f32 v[92:93], v[180:181], v[58:59] op_sel:[0,1]
	v_add_f32_dpp v232, v232, v232 quad_perm:[1,0,3,2] row_mask:0xf bank_mask:0xf
	v_pk_mul_f32 v[94:95], v[182:183], v[60:61] op_sel_hi:[1,0]
	v_add_f32_dpp v233, v233, v233 quad_perm:[1,0,3,2] row_mask:0xf bank_mask:0xf
	v_pk_mul_f32 v[96:97], v[184:185], v[60:61] op_sel:[0,1]
	v_add_f32_dpp v230, v230, v230 quad_perm:[2,3,0,1] row_mask:0xf bank_mask:0xf
	v_pk_fma_f32 v[82:83], v[78:79], v[62:63], v[82:83] op_sel_hi:[1,0,1]
	v_add_f32_dpp v231, v231, v231 quad_perm:[2,3,0,1] row_mask:0xf bank_mask:0xf
	v_pk_fma_f32 v[84:85], v[78:79], v[62:63], v[84:85] op_sel:[0,1,0]
	v_add_f32_dpp v232, v232, v232 quad_perm:[2,3,0,1] row_mask:0xf bank_mask:0xf
	v_pk_fma_f32 v[86:87], v[78:79], v[64:65], v[86:87] op_sel_hi:[1,0,1]
	v_add_f32_dpp v233, v233, v233 quad_perm:[2,3,0,1] row_mask:0xf bank_mask:0xf
	v_pk_fma_f32 v[88:89], v[78:79], v[64:65], v[88:89] op_sel:[0,1,0]
	v_add_f32_dpp v230, v230, v230 row_half_mirror row_mask:0xf bank_mask:0xf
	v_pk_fma_f32 v[90:91], v[78:79], v[66:67], v[90:91] op_sel_hi:[1,0,1]
	v_add_f32_dpp v231, v231, v231 row_half_mirror row_mask:0xf bank_mask:0xf
	v_pk_fma_f32 v[92:93], v[78:79], v[66:67], v[92:93] op_sel:[0,1,0]
	v_add_f32_dpp v232, v232, v232 row_half_mirror row_mask:0xf bank_mask:0xf
	v_pk_fma_f32 v[94:95], v[78:79], v[68:69], v[94:95] op_sel_hi:[1,0,1]
	v_add_f32_dpp v233, v233, v233 row_half_mirror row_mask:0xf bank_mask:0xf
	v_pk_fma_f32 v[96:97], v[78:79], v[68:69], v[96:97] op_sel:[0,1,0]
	ds_read_b128 v[202:205], v240 offset:17152
	ds_read_b128 v[206:209], v240 offset:17168
	ds_read_b128 v[210:213], v241 offset:768
	ds_read_b128 v[214:217], v241 offset:784
	ds_read_b64 v[226:227], v242 offset:768
	s_waitcnt lgkmcnt(10)
	v_pk_fma_f32 v[170:171], v[230:231], v[70:71], v[82:83] op_sel_hi:[1,0,1] neg_lo:[1,0,0] neg_hi:[1,0,0]
	v_pk_fma_f32 v[172:173], v[230:231], v[70:71], v[84:85] op_sel:[0,1,0] neg_lo:[1,0,0] neg_hi:[1,0,0]
	v_pk_fma_f32 v[174:175], v[230:231], v[72:73], v[86:87] op_sel_hi:[1,0,1] neg_lo:[1,0,0] neg_hi:[1,0,0]
	v_pk_fma_f32 v[176:177], v[230:231], v[72:73], v[88:89] op_sel:[0,1,0] neg_lo:[1,0,0] neg_hi:[1,0,0]
	v_pk_fma_f32 v[178:179], v[230:231], v[74:75], v[90:91] op_sel_hi:[1,0,1] neg_lo:[1,0,0] neg_hi:[1,0,0]
	v_pk_fma_f32 v[180:181], v[230:231], v[74:75], v[92:93] op_sel:[0,1,0] neg_lo:[1,0,0] neg_hi:[1,0,0]
	v_pk_fma_f32 v[182:183], v[230:231], v[76:77], v[94:95] op_sel_hi:[1,0,1] neg_lo:[1,0,0] neg_hi:[1,0,0]
	v_pk_fma_f32 v[184:185], v[230:231], v[76:77], v[96:97] op_sel:[0,1,0] neg_lo:[1,0,0] neg_hi:[1,0,0]
	v_pk_fma_f32 v[234:235], v[230:231], v[80:81], v[232:233] op_sel_hi:[1,0,1] neg_lo:[1,0,0] neg_hi:[1,0,0]
	v_pk_fma_f32 v[234:235], v[78:79], v[80:81], v[234:235] op_sel:[0,1,0]
	ds_read_b128 v[218:221], v240 offset:49920
	ds_read_b128 v[222:225], v240 offset:49936
	ds_read_b64 v[228:229], v243 offset:24
	s_mov_b64 exec, s[60:61]
	ds_write_b64 v242, v[234:235] offset:16896
	s_mov_b64 exec, -1
	s_waitcnt lgkmcnt(9)
	v_pk_mul_f32 v[230:231], v[170:171], v[186:187] op_sel_hi:[1,0]
	v_pk_mul_f32 v[232:233], v[170:171], v[194:195] op_sel_hi:[1,0]
	v_pk_fma_f32 v[230:231], v[172:173], v[186:187], v[230:231] op_sel:[0,1,0]
	v_pk_fma_f32 v[232:233], v[172:173], v[194:195], v[232:233] op_sel:[0,1,0]
	v_pk_fma_f32 v[230:231], v[174:175], v[188:189], v[230:231] op_sel_hi:[1,0,1]
	v_pk_fma_f32 v[232:233], v[174:175], v[196:197], v[232:233] op_sel_hi:[1,0,1]
	v_pk_fma_f32 v[230:231], v[176:177], v[188:189], v[230:231] op_sel:[0,1,0]
	v_pk_fma_f32 v[232:233], v[176:177], v[196:197], v[232:233] op_sel:[0,1,0]
	v_pk_fma_f32 v[230:231], v[178:179], v[190:191], v[230:231] op_sel_hi:[1,0,1]
	v_pk_fma_f32 v[232:233], v[178:179], v[198:199], v[232:233] op_sel_hi:[1,0,1]
	v_pk_fma_f32 v[230:231], v[180:181], v[190:191], v[230:231] op_sel:[0,1,0]
	v_pk_fma_f32 v[232:233], v[180:181], v[198:199], v[232:233] op_sel:[0,1,0]
	v_pk_fma_f32 v[230:231], v[182:183], v[192:193], v[230:231] op_sel_hi:[1,0,1]
	v_pk_fma_f32 v[232:233], v[182:183], v[200:201], v[232:233] op_sel_hi:[1,0,1]
	v_pk_fma_f32 v[230:231], v[184:185], v[192:193], v[230:231] op_sel:[0,1,0]
	v_pk_fma_f32 v[232:233], v[184:185], v[200:201], v[232:233] op_sel:[0,1,0]
	ds_read_b128 v[38:41], v240 offset:33792
	ds_read_b128 v[42:45], v240 offset:33808
	ds_read_b128 v[46:49], v240 offset:1024
	ds_read_b128 v[50:53], v240 offset:1040
	s_waitcnt lgkmcnt(8)
; __device__ __forceinline__ void phase_rw_scan(KP P, const Ctx& c) {
;     ...
;             RW_LLOAD(A, 0);
; #pragma unroll 1
;             for (int tk = 0; tk < 64; tk += 2) {
;                 RW_LLOAD(B, tk + 1);
;                 RW_STEP(A, tk);
;                 RW_LLOAD(A, (tk + 2) & 63);
;                 RW_STEP(B, tk + 1);
;             }
	v_pk_mul_f32 v[82:83], v[170:171], v[202:203] op_sel_hi:[1,0]
	v_pk_mul_f32 v[84:85], v[172:173], v[202:203] op_sel:[0,1]
	v_pk_mul_f32 v[86:87], v[174:175], v[204:205] op_sel_hi:[1,0]
	v_pk_mul_f32 v[88:89], v[176:177], v[204:205] op_sel:[0,1]
	v_add_f32_dpp v230, v230, v230 quad_perm:[1,0,3,2] row_mask:0xf bank_mask:0xf
	v_pk_mul_f32 v[90:91], v[178:179], v[206:207] op_sel_hi:[1,0]
	v_add_f32_dpp v231, v231, v231 quad_perm:[1,0,3,2] row_mask:0xf bank_mask:0xf
	v_pk_mul_f32 v[92:93], v[180:181], v[206:207] op_sel:[0,1]
	v_add_f32_dpp v232, v232, v232 quad_perm:[1,0,3,2] row_mask:0xf bank_mask:0xf
	v_pk_mul_f32 v[94:95], v[182:183], v[208:209] op_sel_hi:[1,0]
	v_add_f32_dpp v233, v233, v233 quad_perm:[1,0,3,2] row_mask:0xf bank_mask:0xf
	v_pk_mul_f32 v[96:97], v[184:185], v[208:209] op_sel:[0,1]
	v_add_f32_dpp v230, v230, v230 quad_perm:[2,3,0,1] row_mask:0xf bank_mask:0xf
	v_pk_fma_f32 v[82:83], v[226:227], v[210:211], v[82:83] op_sel_hi:[1,0,1]
	v_add_f32_dpp v231, v231, v231 quad_perm:[2,3,0,1] row_mask:0xf bank_mask:0xf
	v_pk_fma_f32 v[84:85], v[226:227], v[210:211], v[84:85] op_sel:[0,1,0]
	v_add_f32_dpp v232, v232, v232 quad_perm:[2,3,0,1] row_mask:0xf bank_mask:0xf
	v_pk_fma_f32 v[86:87], v[226:227], v[212:213], v[86:87] op_sel_hi:[1,0,1]
	v_add_f32_dpp v233, v233, v233 quad_perm:[2,3,0,1] row_mask:0xf bank_mask:0xf
	v_pk_fma_f32 v[88:89], v[226:227], v[212:213], v[88:89] op_sel:[0,1,0]
	v_add_f32_dpp v230, v230, v230 row_half_mirror row_mask:0xf bank_mask:0xf
	v_pk_fma_f32 v[90:91], v[226:227], v[214:215], v[90:91] op_sel_hi:[1,0,1]
	v_add_f32_dpp v231, v231, v231 row_half_mirror row_mask:0xf bank_mask:0xf
	v_pk_fma_f32 v[92:93], v[226:227], v[214:215], v[92:93] op_sel:[0,1,0]
	v_add_f32_dpp v232, v232, v232 row_half_mirror row_mask:0xf bank_mask:0xf
	v_pk_fma_f32 v[94:95], v[226:227], v[216:217], v[94:95] op_sel_hi:[1,0,1]
	v_add_f32_dpp v233, v233, v233 row_half_mirror row_mask:0xf bank_mask:0xf
	v_pk_fma_f32 v[96:97], v[226:227], v[216:217], v[96:97] op_sel:[0,1,0]
	ds_read_b128 v[54:57], v240 offset:17408
	ds_read_b128 v[58:61], v240 offset:17424
	ds_read_b128 v[62:65], v241 offset:1024
	ds_read_b128 v[66:69], v241 offset:1040
	ds_read_b64 v[78:79], v242 offset:1024
	s_waitcnt lgkmcnt(10)
	v_pk_fma_f32 v[170:171], v[230:231], v[218:219], v[82:83] op_sel_hi:[1,0,1] neg_lo:[1,0,0] neg_hi:[1,0,0]
	v_pk_fma_f32 v[172:173], v[230:231], v[218:219], v[84:85] op_sel:[0,1,0] neg_lo:[1,0,0] neg_hi:[1,0,0]
	v_pk_fma_f32 v[174:175], v[230:231], v[220:221], v[86:87] op_sel_hi:[1,0,1] neg_lo:[1,0,0] neg_hi:[1,0,0]
	v_pk_fma_f32 v[176:177], v[230:231], v[220:221], v[88:89] op_sel:[0,1,0] neg_lo:[1,0,0] neg_hi:[1,0,0]
	v_pk_fma_f32 v[178:179], v[230:231], v[222:223], v[90:91] op_sel_hi:[1,0,1] neg_lo:[1,0,0] neg_hi:[1,0,0]
	v_pk_fma_f32 v[180:181], v[230:231], v[222:223], v[92:93] op_sel:[0,1,0] neg_lo:[1,0,0] neg_hi:[1,0,0]
	v_pk_fma_f32 v[182:183], v[230:231], v[224:225], v[94:95] op_sel_hi:[1,0,1] neg_lo:[1,0,0] neg_hi:[1,0,0]
	v_pk_fma_f32 v[184:185], v[230:231], v[224:225], v[96:97] op_sel:[0,1,0] neg_lo:[1,0,0] neg_hi:[1,0,0]
	v_pk_fma_f32 v[234:235], v[230:231], v[228:229], v[232:233] op_sel_hi:[1,0,1] neg_lo:[1,0,0] neg_hi:[1,0,0]
	v_pk_fma_f32 v[234:235], v[226:227], v[228:229], v[234:235] op_sel:[0,1,0]
	ds_read_b128 v[70:73], v240 offset:50176
	ds_read_b128 v[74:77], v240 offset:50192
	ds_read_b64 v[80:81], v243 offset:32
	s_mov_b64 exec, s[60:61]
	ds_write_b64 v242, v[234:235] offset:17152
	s_mov_b64 exec, -1
	s_waitcnt lgkmcnt(9)
	v_pk_mul_f32 v[230:231], v[170:171], v[38:39] op_sel_hi:[1,0]
	v_pk_mul_f32 v[232:233], v[170:171], v[46:47] op_sel_hi:[1,0]
	v_pk_fma_f32 v[230:231], v[172:173], v[38:39], v[230:231] op_sel:[0,1,0]
	v_pk_fma_f32 v[232:233], v[172:173], v[46:47], v[232:233] op_sel:[0,1,0]
	v_pk_fma_f32 v[230:231], v[174:175], v[40:41], v[230:231] op_sel_hi:[1,0,1]
	v_pk_fma_f32 v[232:233], v[174:175], v[48:49], v[232:233] op_sel_hi:[1,0,1]
	v_pk_fma_f32 v[230:231], v[176:177], v[40:41], v[230:231] op_sel:[0,1,0]
	v_pk_fma_f32 v[232:233], v[176:177], v[48:49], v[232:233] op_sel:[0,1,0]
	v_pk_fma_f32 v[230:231], v[178:179], v[42:43], v[230:231] op_sel_hi:[1,0,1]
	v_pk_fma_f32 v[232:233], v[178:179], v[50:51], v[232:233] op_sel_hi:[1,0,1]
	v_pk_fma_f32 v[230:231], v[180:181], v[42:43], v[230:231] op_sel:[0,1,0]
	v_pk_fma_f32 v[232:233], v[180:181], v[50:51], v[232:233] op_sel:[0,1,0]
	v_pk_fma_f32 v[230:231], v[182:183], v[44:45], v[230:231] op_sel_hi:[1,0,1]
	v_pk_fma_f32 v[232:233], v[182:183], v[52:53], v[232:233] op_sel_hi:[1,0,1]
	v_pk_fma_f32 v[230:231], v[184:185], v[44:45], v[230:231] op_sel:[0,1,0]
	v_pk_fma_f32 v[232:233], v[184:185], v[52:53], v[232:233] op_sel:[0,1,0]
	ds_read_b128 v[186:189], v240 offset:34048
	ds_read_b128 v[190:193], v240 offset:34064
	ds_read_b128 v[194:197], v240 offset:1280
	ds_read_b128 v[198:201], v240 offset:1296
	s_waitcnt lgkmcnt(8)
; __device__ __forceinline__ void phase_rw_scan(KP P, const Ctx& c) {
;     ...
;             RW_LLOAD(A, 0);
; #pragma unroll 1
;             for (int tk = 0; tk < 64; tk += 2) {
;                 RW_LLOAD(B, tk + 1);
;                 RW_STEP(A, tk);
;                 RW_LLOAD(A, (tk + 2) & 63);
;                 RW_STEP(B, tk + 1);
;             }
	v_pk_mul_f32 v[82:83], v[170:171], v[54:55] op_sel_hi:[1,0]
	v_pk_mul_f32 v[84:85], v[172:173], v[54:55] op_sel:[0,1]
	v_pk_mul_f32 v[86:87], v[174:175], v[56:57] op_sel_hi:[1,0]
	v_pk_mul_f32 v[88:89], v[176:177], v[56:57] op_sel:[0,1]
	v_add_f32_dpp v230, v230, v230 quad_perm:[1,0,3,2] row_mask:0xf bank_mask:0xf
	v_pk_mul_f32 v[90:91], v[178:179], v[58:59] op_sel_hi:[1,0]
	v_add_f32_dpp v231, v231, v231 quad_perm:[1,0,3,2] row_mask:0xf bank_mask:0xf
	v_pk_mul_f32 v[92:93], v[180:181], v[58:59] op_sel:[0,1]
	v_add_f32_dpp v232, v232, v232 quad_perm:[1,0,3,2] row_mask:0xf bank_mask:0xf
	v_pk_mul_f32 v[94:95], v[182:183], v[60:61] op_sel_hi:[1,0]
	v_add_f32_dpp v233, v233, v233 quad_perm:[1,0,3,2] row_mask:0xf bank_mask:0xf
	v_pk_mul_f32 v[96:97], v[184:185], v[60:61] op_sel:[0,1]
	v_add_f32_dpp v230, v230, v230 quad_perm:[2,3,0,1] row_mask:0xf bank_mask:0xf
	v_pk_fma_f32 v[82:83], v[78:79], v[62:63], v[82:83] op_sel_hi:[1,0,1]
	v_add_f32_dpp v231, v231, v231 quad_perm:[2,3,0,1] row_mask:0xf bank_mask:0xf
	v_pk_fma_f32 v[84:85], v[78:79], v[62:63], v[84:85] op_sel:[0,1,0]
	v_add_f32_dpp v232, v232, v232 quad_perm:[2,3,0,1] row_mask:0xf bank_mask:0xf
	v_pk_fma_f32 v[86:87], v[78:79], v[64:65], v[86:87] op_sel_hi:[1,0,1]
	v_add_f32_dpp v233, v233, v233 quad_perm:[2,3,0,1] row_mask:0xf bank_mask:0xf
	v_pk_fma_f32 v[88:89], v[78:79], v[64:65], v[88:89] op_sel:[0,1,0]
	v_add_f32_dpp v230, v230, v230 row_half_mirror row_mask:0xf bank_mask:0xf
	v_pk_fma_f32 v[90:91], v[78:79], v[66:67], v[90:91] op_sel_hi:[1,0,1]
	v_add_f32_dpp v231, v231, v231 row_half_mirror row_mask:0xf bank_mask:0xf
	v_pk_fma_f32 v[92:93], v[78:79], v[66:67], v[92:93] op_sel:[0,1,0]
	v_add_f32_dpp v232, v232, v232 row_half_mirror row_mask:0xf bank_mask:0xf
	v_pk_fma_f32 v[94:95], v[78:79], v[68:69], v[94:95] op_sel_hi:[1,0,1]
	v_add_f32_dpp v233, v233, v233 row_half_mirror row_mask:0xf bank_mask:0xf
	v_pk_fma_f32 v[96:97], v[78:79], v[68:69], v[96:97] op_sel:[0,1,0]
	ds_read_b128 v[202:205], v240 offset:17664
	ds_read_b128 v[206:209], v240 offset:17680
	ds_read_b128 v[210:213], v241 offset:1280
	ds_read_b128 v[214:217], v241 offset:1296
	ds_read_b64 v[226:227], v242 offset:1280
	s_waitcnt lgkmcnt(10)
	v_pk_fma_f32 v[170:171], v[230:231], v[70:71], v[82:83] op_sel_hi:[1,0,1] neg_lo:[1,0,0] neg_hi:[1,0,0]
	v_pk_fma_f32 v[172:173], v[230:231], v[70:71], v[84:85] op_sel:[0,1,0] neg_lo:[1,0,0] neg_hi:[1,0,0]
	v_pk_fma_f32 v[174:175], v[230:231], v[72:73], v[86:87] op_sel_hi:[1,0,1] neg_lo:[1,0,0] neg_hi:[1,0,0]
	v_pk_fma_f32 v[176:177], v[230:231], v[72:73], v[88:89] op_sel:[0,1,0] neg_lo:[1,0,0] neg_hi:[1,0,0]
	v_pk_fma_f32 v[178:179], v[230:231], v[74:75], v[90:91] op_sel_hi:[1,0,1] neg_lo:[1,0,0] neg_hi:[1,0,0]
	v_pk_fma_f32 v[180:181], v[230:231], v[74:75], v[92:93] op_sel:[0,1,0] neg_lo:[1,0,0] neg_hi:[1,0,0]
	v_pk_fma_f32 v[182:183], v[230:231], v[76:77], v[94:95] op_sel_hi:[1,0,1] neg_lo:[1,0,0] neg_hi:[1,0,0]
	v_pk_fma_f32 v[184:185], v[230:231], v[76:77], v[96:97] op_sel:[0,1,0] neg_lo:[1,0,0] neg_hi:[1,0,0]
	v_pk_fma_f32 v[234:235], v[230:231], v[80:81], v[232:233] op_sel_hi:[1,0,1] neg_lo:[1,0,0] neg_hi:[1,0,0]
	v_pk_fma_f32 v[234:235], v[78:79], v[80:81], v[234:235] op_sel:[0,1,0]
	ds_read_b128 v[218:221], v240 offset:50432
	ds_read_b128 v[222:225], v240 offset:50448
	ds_read_b64 v[228:229], v243 offset:40
	s_mov_b64 exec, s[60:61]
	ds_write_b64 v242, v[234:235] offset:17408
	s_mov_b64 exec, -1
	s_waitcnt lgkmcnt(9)
	v_pk_mul_f32 v[230:231], v[170:171], v[186:187] op_sel_hi:[1,0]
	v_pk_mul_f32 v[232:233], v[170:171], v[194:195] op_sel_hi:[1,0]
	v_pk_fma_f32 v[230:231], v[172:173], v[186:187], v[230:231] op_sel:[0,1,0]
	v_pk_fma_f32 v[232:233], v[172:173], v[194:195], v[232:233] op_sel:[0,1,0]
	v_pk_fma_f32 v[230:231], v[174:175], v[188:189], v[230:231] op_sel_hi:[1,0,1]
	v_pk_fma_f32 v[232:233], v[174:175], v[196:197], v[232:233] op_sel_hi:[1,0,1]
	v_pk_fma_f32 v[230:231], v[176:177], v[188:189], v[230:231] op_sel:[0,1,0]
	v_pk_fma_f32 v[232:233], v[176:177], v[196:197], v[232:233] op_sel:[0,1,0]
	v_pk_fma_f32 v[230:231], v[178:179], v[190:191], v[230:231] op_sel_hi:[1,0,1]
	v_pk_fma_f32 v[232:233], v[178:179], v[198:199], v[232:233] op_sel_hi:[1,0,1]
	v_pk_fma_f32 v[230:231], v[180:181], v[190:191], v[230:231] op_sel:[0,1,0]
	v_pk_fma_f32 v[232:233], v[180:181], v[198:199], v[232:233] op_sel:[0,1,0]
	v_pk_fma_f32 v[230:231], v[182:183], v[192:193], v[230:231] op_sel_hi:[1,0,1]
	v_pk_fma_f32 v[232:233], v[182:183], v[200:201], v[232:233] op_sel_hi:[1,0,1]
	v_pk_fma_f32 v[230:231], v[184:185], v[192:193], v[230:231] op_sel:[0,1,0]
	v_pk_fma_f32 v[232:233], v[184:185], v[200:201], v[232:233] op_sel:[0,1,0]
	ds_read_b128 v[38:41], v240 offset:34304
	ds_read_b128 v[42:45], v240 offset:34320
	ds_read_b128 v[46:49], v240 offset:1536
	ds_read_b128 v[50:53], v240 offset:1552
	s_waitcnt lgkmcnt(8)
; __device__ __forceinline__ void phase_rw_scan(KP P, const Ctx& c) {
;     ...
;             RW_LLOAD(A, 0);
; #pragma unroll 1
;             for (int tk = 0; tk < 64; tk += 2) {
;                 RW_LLOAD(B, tk + 1);
;                 RW_STEP(A, tk);
;                 RW_LLOAD(A, (tk + 2) & 63);
;                 RW_STEP(B, tk + 1);
;             }
	v_pk_mul_f32 v[82:83], v[170:171], v[202:203] op_sel_hi:[1,0]
	v_pk_mul_f32 v[84:85], v[172:173], v[202:203] op_sel:[0,1]
	v_pk_mul_f32 v[86:87], v[174:175], v[204:205] op_sel_hi:[1,0]
	v_pk_mul_f32 v[88:89], v[176:177], v[204:205] op_sel:[0,1]
	v_add_f32_dpp v230, v230, v230 quad_perm:[1,0,3,2] row_mask:0xf bank_mask:0xf
	v_pk_mul_f32 v[90:91], v[178:179], v[206:207] op_sel_hi:[1,0]
	v_add_f32_dpp v231, v231, v231 quad_perm:[1,0,3,2] row_mask:0xf bank_mask:0xf
	v_pk_mul_f32 v[92:93], v[180:181], v[206:207] op_sel:[0,1]
	v_add_f32_dpp v232, v232, v232 quad_perm:[1,0,3,2] row_mask:0xf bank_mask:0xf
	v_pk_mul_f32 v[94:95], v[182:183], v[208:209] op_sel_hi:[1,0]
	v_add_f32_dpp v233, v233, v233 quad_perm:[1,0,3,2] row_mask:0xf bank_mask:0xf
	v_pk_mul_f32 v[96:97], v[184:185], v[208:209] op_sel:[0,1]
	v_add_f32_dpp v230, v230, v230 quad_perm:[2,3,0,1] row_mask:0xf bank_mask:0xf
	v_pk_fma_f32 v[82:83], v[226:227], v[210:211], v[82:83] op_sel_hi:[1,0,1]
	v_add_f32_dpp v231, v231, v231 quad_perm:[2,3,0,1] row_mask:0xf bank_mask:0xf
	v_pk_fma_f32 v[84:85], v[226:227], v[210:211], v[84:85] op_sel:[0,1,0]
	v_add_f32_dpp v232, v232, v232 quad_perm:[2,3,0,1] row_mask:0xf bank_mask:0xf
	v_pk_fma_f32 v[86:87], v[226:227], v[212:213], v[86:87] op_sel_hi:[1,0,1]
	v_add_f32_dpp v233, v233, v233 quad_perm:[2,3,0,1] row_mask:0xf bank_mask:0xf
	v_pk_fma_f32 v[88:89], v[226:227], v[212:213], v[88:89] op_sel:[0,1,0]
	v_add_f32_dpp v230, v230, v230 row_half_mirror row_mask:0xf bank_mask:0xf
	v_pk_fma_f32 v[90:91], v[226:227], v[214:215], v[90:91] op_sel_hi:[1,0,1]
	v_add_f32_dpp v231, v231, v231 row_half_mirror row_mask:0xf bank_mask:0xf
	v_pk_fma_f32 v[92:93], v[226:227], v[214:215], v[92:93] op_sel:[0,1,0]
	v_add_f32_dpp v232, v232, v232 row_half_mirror row_mask:0xf bank_mask:0xf
	v_pk_fma_f32 v[94:95], v[226:227], v[216:217], v[94:95] op_sel_hi:[1,0,1]
	v_add_f32_dpp v233, v233, v233 row_half_mirror row_mask:0xf bank_mask:0xf
	v_pk_fma_f32 v[96:97], v[226:227], v[216:217], v[96:97] op_sel:[0,1,0]
	ds_read_b128 v[54:57], v240 offset:17920
	ds_read_b128 v[58:61], v240 offset:17936
	ds_read_b128 v[62:65], v241 offset:1536
	ds_read_b128 v[66:69], v241 offset:1552
	ds_read_b64 v[78:79], v242 offset:1536
	s_waitcnt lgkmcnt(10)
	v_pk_fma_f32 v[170:171], v[230:231], v[218:219], v[82:83] op_sel_hi:[1,0,1] neg_lo:[1,0,0] neg_hi:[1,0,0]
	v_pk_fma_f32 v[172:173], v[230:231], v[218:219], v[84:85] op_sel:[0,1,0] neg_lo:[1,0,0] neg_hi:[1,0,0]
	v_pk_fma_f32 v[174:175], v[230:231], v[220:221], v[86:87] op_sel_hi:[1,0,1] neg_lo:[1,0,0] neg_hi:[1,0,0]
	v_pk_fma_f32 v[176:177], v[230:231], v[220:221], v[88:89] op_sel:[0,1,0] neg_lo:[1,0,0] neg_hi:[1,0,0]
	v_pk_fma_f32 v[178:179], v[230:231], v[222:223], v[90:91] op_sel_hi:[1,0,1] neg_lo:[1,0,0] neg_hi:[1,0,0]
	v_pk_fma_f32 v[180:181], v[230:231], v[222:223], v[92:93] op_sel:[0,1,0] neg_lo:[1,0,0] neg_hi:[1,0,0]
	v_pk_fma_f32 v[182:183], v[230:231], v[224:225], v[94:95] op_sel_hi:[1,0,1] neg_lo:[1,0,0] neg_hi:[1,0,0]
	v_pk_fma_f32 v[184:185], v[230:231], v[224:225], v[96:97] op_sel:[0,1,0] neg_lo:[1,0,0] neg_hi:[1,0,0]
	v_pk_fma_f32 v[234:235], v[230:231], v[228:229], v[232:233] op_sel_hi:[1,0,1] neg_lo:[1,0,0] neg_hi:[1,0,0]
	v_pk_fma_f32 v[234:235], v[226:227], v[228:229], v[234:235] op_sel:[0,1,0]
	ds_read_b128 v[70:73], v240 offset:50688
	ds_read_b128 v[74:77], v240 offset:50704
	ds_read_b64 v[80:81], v243 offset:48
	s_mov_b64 exec, s[60:61]
	ds_write_b64 v242, v[234:235] offset:17664
	s_mov_b64 exec, -1
	s_waitcnt lgkmcnt(9)
	v_pk_mul_f32 v[230:231], v[170:171], v[38:39] op_sel_hi:[1,0]
	v_pk_mul_f32 v[232:233], v[170:171], v[46:47] op_sel_hi:[1,0]
	v_pk_fma_f32 v[230:231], v[172:173], v[38:39], v[230:231] op_sel:[0,1,0]
	v_pk_fma_f32 v[232:233], v[172:173], v[46:47], v[232:233] op_sel:[0,1,0]
	v_pk_fma_f32 v[230:231], v[174:175], v[40:41], v[230:231] op_sel_hi:[1,0,1]
	v_pk_fma_f32 v[232:233], v[174:175], v[48:49], v[232:233] op_sel_hi:[1,0,1]
	v_pk_fma_f32 v[230:231], v[176:177], v[40:41], v[230:231] op_sel:[0,1,0]
	v_pk_fma_f32 v[232:233], v[176:177], v[48:49], v[232:233] op_sel:[0,1,0]
	v_pk_fma_f32 v[230:231], v[178:179], v[42:43], v[230:231] op_sel_hi:[1,0,1]
	v_pk_fma_f32 v[232:233], v[178:179], v[50:51], v[232:233] op_sel_hi:[1,0,1]
	v_pk_fma_f32 v[230:231], v[180:181], v[42:43], v[230:231] op_sel:[0,1,0]
	v_pk_fma_f32 v[232:233], v[180:181], v[50:51], v[232:233] op_sel:[0,1,0]
	v_pk_fma_f32 v[230:231], v[182:183], v[44:45], v[230:231] op_sel_hi:[1,0,1]
	v_pk_fma_f32 v[232:233], v[182:183], v[52:53], v[232:233] op_sel_hi:[1,0,1]
	v_pk_fma_f32 v[230:231], v[184:185], v[44:45], v[230:231] op_sel:[0,1,0]
	v_pk_fma_f32 v[232:233], v[184:185], v[52:53], v[232:233] op_sel:[0,1,0]
	ds_read_b128 v[186:189], v240 offset:34560
	ds_read_b128 v[190:193], v240 offset:34576
	ds_read_b128 v[194:197], v240 offset:1792
	ds_read_b128 v[198:201], v240 offset:1808
	s_waitcnt lgkmcnt(8)
; __device__ __forceinline__ void phase_rw_scan(KP P, const Ctx& c) {
;     ...
;             RW_LLOAD(A, 0);
; #pragma unroll 1
;             for (int tk = 0; tk < 64; tk += 2) {
;                 RW_LLOAD(B, tk + 1);
;                 RW_STEP(A, tk);
;                 RW_LLOAD(A, (tk + 2) & 63);
;                 RW_STEP(B, tk + 1);
;             }
	v_pk_mul_f32 v[82:83], v[170:171], v[54:55] op_sel_hi:[1,0]
	v_pk_mul_f32 v[84:85], v[172:173], v[54:55] op_sel:[0,1]
	v_pk_mul_f32 v[86:87], v[174:175], v[56:57] op_sel_hi:[1,0]
	v_pk_mul_f32 v[88:89], v[176:177], v[56:57] op_sel:[0,1]
	v_add_f32_dpp v230, v230, v230 quad_perm:[1,0,3,2] row_mask:0xf bank_mask:0xf
	v_pk_mul_f32 v[90:91], v[178:179], v[58:59] op_sel_hi:[1,0]
	v_add_f32_dpp v231, v231, v231 quad_perm:[1,0,3,2] row_mask:0xf bank_mask:0xf
	v_pk_mul_f32 v[92:93], v[180:181], v[58:59] op_sel:[0,1]
	v_add_f32_dpp v232, v232, v232 quad_perm:[1,0,3,2] row_mask:0xf bank_mask:0xf
	v_pk_mul_f32 v[94:95], v[182:183], v[60:61] op_sel_hi:[1,0]
	v_add_f32_dpp v233, v233, v233 quad_perm:[1,0,3,2] row_mask:0xf bank_mask:0xf
	v_pk_mul_f32 v[96:97], v[184:185], v[60:61] op_sel:[0,1]
	v_add_f32_dpp v230, v230, v230 quad_perm:[2,3,0,1] row_mask:0xf bank_mask:0xf
	v_pk_fma_f32 v[82:83], v[78:79], v[62:63], v[82:83] op_sel_hi:[1,0,1]
	v_add_f32_dpp v231, v231, v231 quad_perm:[2,3,0,1] row_mask:0xf bank_mask:0xf
	v_pk_fma_f32 v[84:85], v[78:79], v[62:63], v[84:85] op_sel:[0,1,0]
	v_add_f32_dpp v232, v232, v232 quad_perm:[2,3,0,1] row_mask:0xf bank_mask:0xf
	v_pk_fma_f32 v[86:87], v[78:79], v[64:65], v[86:87] op_sel_hi:[1,0,1]
	v_add_f32_dpp v233, v233, v233 quad_perm:[2,3,0,1] row_mask:0xf bank_mask:0xf
	v_pk_fma_f32 v[88:89], v[78:79], v[64:65], v[88:89] op_sel:[0,1,0]
	v_add_f32_dpp v230, v230, v230 row_half_mirror row_mask:0xf bank_mask:0xf
	v_pk_fma_f32 v[90:91], v[78:79], v[66:67], v[90:91] op_sel_hi:[1,0,1]
	v_add_f32_dpp v231, v231, v231 row_half_mirror row_mask:0xf bank_mask:0xf
	v_pk_fma_f32 v[92:93], v[78:79], v[66:67], v[92:93] op_sel:[0,1,0]
	v_add_f32_dpp v232, v232, v232 row_half_mirror row_mask:0xf bank_mask:0xf
	v_pk_fma_f32 v[94:95], v[78:79], v[68:69], v[94:95] op_sel_hi:[1,0,1]
	v_add_f32_dpp v233, v233, v233 row_half_mirror row_mask:0xf bank_mask:0xf
	v_pk_fma_f32 v[96:97], v[78:79], v[68:69], v[96:97] op_sel:[0,1,0]
	ds_read_b128 v[202:205], v240 offset:18176
	ds_read_b128 v[206:209], v240 offset:18192
	ds_read_b128 v[210:213], v241 offset:1792
	ds_read_b128 v[214:217], v241 offset:1808
	ds_read_b64 v[226:227], v242 offset:1792
	s_waitcnt lgkmcnt(10)
	v_pk_fma_f32 v[170:171], v[230:231], v[70:71], v[82:83] op_sel_hi:[1,0,1] neg_lo:[1,0,0] neg_hi:[1,0,0]
	v_pk_fma_f32 v[172:173], v[230:231], v[70:71], v[84:85] op_sel:[0,1,0] neg_lo:[1,0,0] neg_hi:[1,0,0]
	v_pk_fma_f32 v[174:175], v[230:231], v[72:73], v[86:87] op_sel_hi:[1,0,1] neg_lo:[1,0,0] neg_hi:[1,0,0]
	v_pk_fma_f32 v[176:177], v[230:231], v[72:73], v[88:89] op_sel:[0,1,0] neg_lo:[1,0,0] neg_hi:[1,0,0]
	v_pk_fma_f32 v[178:179], v[230:231], v[74:75], v[90:91] op_sel_hi:[1,0,1] neg_lo:[1,0,0] neg_hi:[1,0,0]
	v_pk_fma_f32 v[180:181], v[230:231], v[74:75], v[92:93] op_sel:[0,1,0] neg_lo:[1,0,0] neg_hi:[1,0,0]
	v_pk_fma_f32 v[182:183], v[230:231], v[76:77], v[94:95] op_sel_hi:[1,0,1] neg_lo:[1,0,0] neg_hi:[1,0,0]
	v_pk_fma_f32 v[184:185], v[230:231], v[76:77], v[96:97] op_sel:[0,1,0] neg_lo:[1,0,0] neg_hi:[1,0,0]
	v_pk_fma_f32 v[234:235], v[230:231], v[80:81], v[232:233] op_sel_hi:[1,0,1] neg_lo:[1,0,0] neg_hi:[1,0,0]
	v_pk_fma_f32 v[234:235], v[78:79], v[80:81], v[234:235] op_sel:[0,1,0]
	ds_read_b128 v[218:221], v240 offset:50944
	ds_read_b128 v[222:225], v240 offset:50960
	ds_read_b64 v[228:229], v243 offset:56
	s_mov_b64 exec, s[60:61]
	ds_write_b64 v242, v[234:235] offset:17920
	s_mov_b64 exec, -1
	s_waitcnt lgkmcnt(9)
	v_pk_mul_f32 v[230:231], v[170:171], v[186:187] op_sel_hi:[1,0]
	v_pk_mul_f32 v[232:233], v[170:171], v[194:195] op_sel_hi:[1,0]
	v_pk_fma_f32 v[230:231], v[172:173], v[186:187], v[230:231] op_sel:[0,1,0]
	v_pk_fma_f32 v[232:233], v[172:173], v[194:195], v[232:233] op_sel:[0,1,0]
	v_pk_fma_f32 v[230:231], v[174:175], v[188:189], v[230:231] op_sel_hi:[1,0,1]
	v_pk_fma_f32 v[232:233], v[174:175], v[196:197], v[232:233] op_sel_hi:[1,0,1]
	v_pk_fma_f32 v[230:231], v[176:177], v[188:189], v[230:231] op_sel:[0,1,0]
	v_pk_fma_f32 v[232:233], v[176:177], v[196:197], v[232:233] op_sel:[0,1,0]
	v_pk_fma_f32 v[230:231], v[178:179], v[190:191], v[230:231] op_sel_hi:[1,0,1]
	v_pk_fma_f32 v[232:233], v[178:179], v[198:199], v[232:233] op_sel_hi:[1,0,1]
	v_pk_fma_f32 v[230:231], v[180:181], v[190:191], v[230:231] op_sel:[0,1,0]
	v_pk_fma_f32 v[232:233], v[180:181], v[198:199], v[232:233] op_sel:[0,1,0]
	v_pk_fma_f32 v[230:231], v[182:183], v[192:193], v[230:231] op_sel_hi:[1,0,1]
	v_pk_fma_f32 v[232:233], v[182:183], v[200:201], v[232:233] op_sel_hi:[1,0,1]
	v_pk_fma_f32 v[230:231], v[184:185], v[192:193], v[230:231] op_sel:[0,1,0]
	v_pk_fma_f32 v[232:233], v[184:185], v[200:201], v[232:233] op_sel:[0,1,0]
	ds_read_b128 v[38:41], v240 offset:34816
	ds_read_b128 v[42:45], v240 offset:34832
	ds_read_b128 v[46:49], v240 offset:2048
	ds_read_b128 v[50:53], v240 offset:2064
	s_waitcnt lgkmcnt(8)
; __device__ __forceinline__ void phase_rw_scan(KP P, const Ctx& c) {
;     ...
;             RW_LLOAD(A, 0);
; #pragma unroll 1
;             for (int tk = 0; tk < 64; tk += 2) {
;                 RW_LLOAD(B, tk + 1);
;                 RW_STEP(A, tk);
;                 RW_LLOAD(A, (tk + 2) & 63);
;                 RW_STEP(B, tk + 1);
;             }
	v_pk_mul_f32 v[82:83], v[170:171], v[202:203] op_sel_hi:[1,0]
	v_pk_mul_f32 v[84:85], v[172:173], v[202:203] op_sel:[0,1]
	v_pk_mul_f32 v[86:87], v[174:175], v[204:205] op_sel_hi:[1,0]
	v_pk_mul_f32 v[88:89], v[176:177], v[204:205] op_sel:[0,1]
	v_add_f32_dpp v230, v230, v230 quad_perm:[1,0,3,2] row_mask:0xf bank_mask:0xf
	v_pk_mul_f32 v[90:91], v[178:179], v[206:207] op_sel_hi:[1,0]
	v_add_f32_dpp v231, v231, v231 quad_perm:[1,0,3,2] row_mask:0xf bank_mask:0xf
	v_pk_mul_f32 v[92:93], v[180:181], v[206:207] op_sel:[0,1]
	v_add_f32_dpp v232, v232, v232 quad_perm:[1,0,3,2] row_mask:0xf bank_mask:0xf
	v_pk_mul_f32 v[94:95], v[182:183], v[208:209] op_sel_hi:[1,0]
	v_add_f32_dpp v233, v233, v233 quad_perm:[1,0,3,2] row_mask:0xf bank_mask:0xf
	v_pk_mul_f32 v[96:97], v[184:185], v[208:209] op_sel:[0,1]
	v_add_f32_dpp v230, v230, v230 quad_perm:[2,3,0,1] row_mask:0xf bank_mask:0xf
	v_pk_fma_f32 v[82:83], v[226:227], v[210:211], v[82:83] op_sel_hi:[1,0,1]
	v_add_f32_dpp v231, v231, v231 quad_perm:[2,3,0,1] row_mask:0xf bank_mask:0xf
	v_pk_fma_f32 v[84:85], v[226:227], v[210:211], v[84:85] op_sel:[0,1,0]
	v_add_f32_dpp v232, v232, v232 quad_perm:[2,3,0,1] row_mask:0xf bank_mask:0xf
	v_pk_fma_f32 v[86:87], v[226:227], v[212:213], v[86:87] op_sel_hi:[1,0,1]
	v_add_f32_dpp v233, v233, v233 quad_perm:[2,3,0,1] row_mask:0xf bank_mask:0xf
	v_pk_fma_f32 v[88:89], v[226:227], v[212:213], v[88:89] op_sel:[0,1,0]
	v_add_f32_dpp v230, v230, v230 row_half_mirror row_mask:0xf bank_mask:0xf
	v_pk_fma_f32 v[90:91], v[226:227], v[214:215], v[90:91] op_sel_hi:[1,0,1]
	v_add_f32_dpp v231, v231, v231 row_half_mirror row_mask:0xf bank_mask:0xf
	v_pk_fma_f32 v[92:93], v[226:227], v[214:215], v[92:93] op_sel:[0,1,0]
	v_add_f32_dpp v232, v232, v232 row_half_mirror row_mask:0xf bank_mask:0xf
	v_pk_fma_f32 v[94:95], v[226:227], v[216:217], v[94:95] op_sel_hi:[1,0,1]
	v_add_f32_dpp v233, v233, v233 row_half_mirror row_mask:0xf bank_mask:0xf
	v_pk_fma_f32 v[96:97], v[226:227], v[216:217], v[96:97] op_sel:[0,1,0]
	ds_read_b128 v[54:57], v240 offset:18432
	ds_read_b128 v[58:61], v240 offset:18448
	ds_read_b128 v[62:65], v241 offset:2048
	ds_read_b128 v[66:69], v241 offset:2064
	ds_read_b64 v[78:79], v242 offset:2048
	s_waitcnt lgkmcnt(10)
	v_pk_fma_f32 v[170:171], v[230:231], v[218:219], v[82:83] op_sel_hi:[1,0,1] neg_lo:[1,0,0] neg_hi:[1,0,0]
	v_pk_fma_f32 v[172:173], v[230:231], v[218:219], v[84:85] op_sel:[0,1,0] neg_lo:[1,0,0] neg_hi:[1,0,0]
	v_pk_fma_f32 v[174:175], v[230:231], v[220:221], v[86:87] op_sel_hi:[1,0,1] neg_lo:[1,0,0] neg_hi:[1,0,0]
	v_pk_fma_f32 v[176:177], v[230:231], v[220:221], v[88:89] op_sel:[0,1,0] neg_lo:[1,0,0] neg_hi:[1,0,0]
	v_pk_fma_f32 v[178:179], v[230:231], v[222:223], v[90:91] op_sel_hi:[1,0,1] neg_lo:[1,0,0] neg_hi:[1,0,0]
	v_pk_fma_f32 v[180:181], v[230:231], v[222:223], v[92:93] op_sel:[0,1,0] neg_lo:[1,0,0] neg_hi:[1,0,0]
	v_pk_fma_f32 v[182:183], v[230:231], v[224:225], v[94:95] op_sel_hi:[1,0,1] neg_lo:[1,0,0] neg_hi:[1,0,0]
	v_pk_fma_f32 v[184:185], v[230:231], v[224:225], v[96:97] op_sel:[0,1,0] neg_lo:[1,0,0] neg_hi:[1,0,0]
	v_pk_fma_f32 v[234:235], v[230:231], v[228:229], v[232:233] op_sel_hi:[1,0,1] neg_lo:[1,0,0] neg_hi:[1,0,0]
	v_pk_fma_f32 v[234:235], v[226:227], v[228:229], v[234:235] op_sel:[0,1,0]
	ds_read_b128 v[70:73], v240 offset:51200
	ds_read_b128 v[74:77], v240 offset:51216
	ds_read_b64 v[80:81], v243 offset:64
	s_mov_b64 exec, s[60:61]
	ds_write_b64 v242, v[234:235] offset:18176
	s_mov_b64 exec, -1
	v_add_u32_e32 v240, 0x800, v240
	v_add_u32_e32 v241, 0x800, v241
	v_add_u32_e32 v242, 0x800, v242
	v_add_u32_e32 v243, 0x40, v243
	s_add_i32 s62, s62, 1
	s_cmp_lt_u32 s62, 8
	s_cbranch_scc1 .Lrw_loop
	s_branch .LBB0_1754
